# adds: P7 per-unit vmcnt(0) in the accumulator clear removed (store drain no longer blocks the K-loop start)
# speedup vs baseline: 1.0040x; 1.0010x over previous
.LBB0_412:
	s_cmpk_gt_i32 s18, 0x157
	s_mov_b32 s14, 55
	s_cbranch_scc1 .LBB0_424
	s_cmpk_lt_i32 s18, 0x100
	s_mov_b64 s[10:11], -1
	s_cbranch_scc0 .LBB0_418
	global_load_dwordx4 v[16:19], v[34:35], off offset:16
	global_load_dwordx4 v[20:23], v[34:35], off
	global_load_dwordx4 v[0:3], v[34:35], off offset:2064
	global_load_dwordx4 v[8:11], v[34:35], off offset:2048
	global_load_dwordx4 v[4:7], v[36:37], off offset:16
	global_load_dwordx4 v[12:15], v[36:37], off
	s_lshl_b32 s10, s18, 6
	s_add_i32 s10, s10, s3
	s_ashr_i32 s11, s10, 31
	s_lshl_b64 s[12:13], s[10:11], 10
	s_lshl_b64 s[14:15], s[10:11], 11
	s_add_u32 s20, s12, 0x1000
	s_addc_u32 s21, s13, 0
	v_lshl_add_u64 v[44:45], v[26:27], 0, s[12:13]
	v_lshl_add_u64 v[46:47], v[28:29], 0, s[12:13]
	v_lshl_add_u64 v[48:49], v[30:31], 0, s[12:13]
	v_lshl_add_u64 v[50:51], v[26:27], 0, s[20:21]
	v_lshl_add_u64 v[52:53], v[28:29], 0, s[20:21]
	v_lshl_add_u64 v[54:55], v[30:31], 0, s[20:21]
	global_load_dwordx4 v[64:67], v[44:45], off offset:-2048
	global_load_dwordx4 v[68:71], v[46:47], off offset:-2048
	global_load_dwordx4 v[72:75], v[44:45], off offset:-1024
	global_load_dwordx4 v[76:79], v[46:47], off offset:-1024
	global_load_dwordx4 v[96:99], v[44:45], off
	global_load_dwordx4 v[100:103], v[46:47], off
	global_load_dwordx4 v[104:107], v[48:49], off
	global_load_dwordx4 v[108:111], v[44:45], off offset:1024
	global_load_dwordx4 v[112:115], v[46:47], off offset:1024
	global_load_dwordx4 v[116:119], v[48:49], off offset:1024
	global_load_dwordx4 v[120:123], v[44:45], off offset:2048
	global_load_dwordx4 v[124:127], v[46:47], off offset:2048
	global_load_dwordx4 v[128:131], v[48:49], off offset:2048
	global_load_dwordx4 v[132:135], v[44:45], off offset:3072
	global_load_dwordx4 v[136:139], v[46:47], off offset:3072
	global_load_dwordx4 v[140:143], v[48:49], off offset:3072
	global_load_dwordx4 v[144:147], v[50:51], off
	global_load_dwordx4 v[148:151], v[52:53], off
	global_load_dwordx4 v[152:155], v[54:55], off
	global_load_dwordx4 v[156:159], v[50:51], off offset:1024
	global_load_dwordx4 v[160:163], v[52:53], off offset:1024
	global_load_dwordx4 v[164:167], v[54:55], off offset:1024
	global_load_dwordx4 v[168:171], v[50:51], off offset:2048
	global_load_dwordx4 v[172:175], v[52:53], off offset:2048
	global_load_dwordx4 v[176:179], v[54:55], off offset:2048
	global_load_dwordx4 v[180:183], v[50:51], off offset:3072
	global_load_dwordx4 v[184:187], v[52:53], off offset:3072
	global_load_dwordx4 v[188:191], v[54:55], off offset:3072
	v_lshl_add_u64 v[56:57], v[32:33], 0, s[14:15]
	s_add_u32 s14, s14, 0x1000
	s_addc_u32 s15, s15, 0
	v_lshl_add_u64 v[58:59], v[32:33], 0, s[14:15]
	s_add_u32 s14, s14, 0x1000
	s_addc_u32 s15, s15, 0
	v_lshl_add_u64 v[60:61], v[32:33], 0, s[14:15]
	s_add_u32 s14, s14, 0x1000
	s_addc_u32 s15, s15, 0
	v_lshl_add_u64 v[62:63], v[32:33], 0, s[14:15]
	s_waitcnt vmcnt(24)
	v_lshlrev_b32_e32 v216, 16, v64
	v_and_b32_e32 v217, 0xffff0000, v64
	v_lshlrev_b32_e32 v218, 16, v65
	v_and_b32_e32 v219, 0xffff0000, v65
	v_lshlrev_b32_e32 v220, 16, v66
	v_and_b32_e32 v221, 0xffff0000, v66
	v_lshlrev_b32_e32 v222, 16, v67
	v_and_b32_e32 v223, 0xffff0000, v67
	v_lshlrev_b32_e32 v224, 16, v68
	v_and_b32_e32 v225, 0xffff0000, v68
	v_lshlrev_b32_e32 v226, 16, v69
	v_and_b32_e32 v227, 0xffff0000, v69
	v_lshlrev_b32_e32 v228, 16, v70
	v_and_b32_e32 v229, 0xffff0000, v70
	v_lshlrev_b32_e32 v230, 16, v71
	v_and_b32_e32 v231, 0xffff0000, v71
	v_pk_mul_f32 v[192:193], v[216:217], v[224:225]
	v_pk_mul_f32 v[194:195], v[218:219], v[226:227]
	v_pk_mul_f32 v[196:197], v[220:221], v[228:229]
	v_pk_mul_f32 v[198:199], v[222:223], v[230:231]
	v_lshlrev_b32_e32 v216, 16, v72
	v_and_b32_e32 v217, 0xffff0000, v72
	v_lshlrev_b32_e32 v218, 16, v73
	v_and_b32_e32 v219, 0xffff0000, v73
	v_lshlrev_b32_e32 v220, 16, v74
	v_and_b32_e32 v221, 0xffff0000, v74
	v_lshlrev_b32_e32 v222, 16, v75
	v_and_b32_e32 v223, 0xffff0000, v75
	v_lshlrev_b32_e32 v224, 16, v76
	v_and_b32_e32 v225, 0xffff0000, v76
	v_lshlrev_b32_e32 v226, 16, v77
	v_and_b32_e32 v227, 0xffff0000, v77
	v_lshlrev_b32_e32 v228, 16, v78
	v_and_b32_e32 v229, 0xffff0000, v78
	v_lshlrev_b32_e32 v230, 16, v79
	v_and_b32_e32 v231, 0xffff0000, v79
	v_pk_mul_f32 v[200:201], v[216:217], v[224:225]
	v_pk_mul_f32 v[202:203], v[218:219], v[226:227]
	v_pk_mul_f32 v[204:205], v[220:221], v[228:229]
	v_pk_mul_f32 v[206:207], v[222:223], v[230:231]
	s_and_b32 s11, s10, 0x1ff8
	s_cmp_eq_u32 s11, 0
	s_cbranch_scc0 .Lconv_tail_hist_ok
	v_mov_b32_e32 v192, 0
	v_mov_b32_e32 v193, 0
	v_mov_b32_e32 v194, 0
	v_mov_b32_e32 v195, 0
	v_mov_b32_e32 v196, 0
	v_mov_b32_e32 v197, 0
	v_mov_b32_e32 v198, 0
	v_mov_b32_e32 v199, 0
	v_mov_b32_e32 v200, 0
	v_mov_b32_e32 v201, 0
	v_mov_b32_e32 v202, 0
	v_mov_b32_e32 v203, 0
	v_mov_b32_e32 v204, 0
	v_mov_b32_e32 v205, 0
	v_mov_b32_e32 v206, 0
	v_mov_b32_e32 v207, 0
.Lconv_tail_hist_ok:
	s_waitcnt vmcnt(21)
	v_lshlrev_b32_e32 v216, 16, v96
	v_and_b32_e32 v217, 0xffff0000, v96
	v_lshlrev_b32_e32 v218, 16, v97
	v_and_b32_e32 v219, 0xffff0000, v97
	v_lshlrev_b32_e32 v220, 16, v98
	v_and_b32_e32 v221, 0xffff0000, v98
	v_lshlrev_b32_e32 v222, 16, v99
	v_and_b32_e32 v223, 0xffff0000, v99
	v_lshlrev_b32_e32 v224, 16, v100
	v_and_b32_e32 v225, 0xffff0000, v100
	v_lshlrev_b32_e32 v226, 16, v101
	v_and_b32_e32 v227, 0xffff0000, v101
	v_lshlrev_b32_e32 v228, 16, v102
	v_and_b32_e32 v229, 0xffff0000, v102
	v_lshlrev_b32_e32 v230, 16, v103
	v_and_b32_e32 v231, 0xffff0000, v103
	v_pk_mul_f32 v[208:209], v[216:217], v[224:225]
	v_pk_mul_f32 v[210:211], v[218:219], v[226:227]
	v_pk_mul_f32 v[212:213], v[220:221], v[228:229]
	v_pk_mul_f32 v[214:215], v[222:223], v[230:231]
	v_lshlrev_b32_e32 v80, 16, v104
	v_and_b32_e32 v81, 0xffff0000, v104
	v_lshlrev_b32_e32 v82, 16, v105
	v_and_b32_e32 v83, 0xffff0000, v105
	v_lshlrev_b32_e32 v84, 16, v106
	v_and_b32_e32 v85, 0xffff0000, v106
	v_lshlrev_b32_e32 v86, 16, v107
	v_and_b32_e32 v87, 0xffff0000, v107
	v_pk_mul_f32 v[64:65], v[20:21], v[192:193]
	v_pk_mul_f32 v[66:67], v[22:23], v[194:195]
	v_pk_mul_f32 v[68:69], v[16:17], v[196:197]
	v_pk_mul_f32 v[70:71], v[18:19], v[198:199]
	v_pk_mul_f32 v[72:73], v[8:9], v[200:201]
	v_pk_mul_f32 v[74:75], v[10:11], v[202:203]
	v_pk_mul_f32 v[76:77], v[0:1], v[204:205]
	v_pk_mul_f32 v[78:79], v[2:3], v[206:207]
	v_pk_add_f32 v[64:65], v[64:65], v[72:73]
	v_pk_add_f32 v[66:67], v[66:67], v[74:75]
	v_pk_add_f32 v[68:69], v[68:69], v[76:77]
	v_pk_add_f32 v[70:71], v[70:71], v[78:79]
	v_pk_fma_f32 v[64:65], v[208:209], v[12:13], v[64:65]
	v_pk_fma_f32 v[66:67], v[210:211], v[14:15], v[66:67]
	v_pk_fma_f32 v[68:69], v[212:213], v[4:5], v[68:69]
	v_pk_fma_f32 v[70:71], v[214:215], v[6:7], v[70:71]
	v_pk_mul_f32 v[64:65], v[64:65], v[80:81]
	v_pk_mul_f32 v[66:67], v[66:67], v[82:83]
	v_pk_mul_f32 v[68:69], v[68:69], v[84:85]
	v_pk_mul_f32 v[70:71], v[70:71], v[86:87]
	v_cvt_pk_bf16_f32 v88, v64, v65
	v_cvt_pk_bf16_f32 v89, v66, v67
	v_cvt_pk_bf16_f32 v90, v68, v69
	v_cvt_pk_bf16_f32 v91, v70, v71
	global_store_dwordx4 v[56:57], v[88:91], off
	s_waitcnt vmcnt(19)
	v_lshlrev_b32_e32 v216, 16, v108
	v_and_b32_e32 v217, 0xffff0000, v108
	v_lshlrev_b32_e32 v218, 16, v109
	v_and_b32_e32 v219, 0xffff0000, v109
	v_lshlrev_b32_e32 v220, 16, v110
	v_and_b32_e32 v221, 0xffff0000, v110
	v_lshlrev_b32_e32 v222, 16, v111
	v_and_b32_e32 v223, 0xffff0000, v111
	v_lshlrev_b32_e32 v224, 16, v112
	v_and_b32_e32 v225, 0xffff0000, v112
	v_lshlrev_b32_e32 v226, 16, v113
	v_and_b32_e32 v227, 0xffff0000, v113
	v_lshlrev_b32_e32 v228, 16, v114
	v_and_b32_e32 v229, 0xffff0000, v114
	v_lshlrev_b32_e32 v230, 16, v115
	v_and_b32_e32 v231, 0xffff0000, v115
	v_pk_mul_f32 v[192:193], v[216:217], v[224:225]
	v_pk_mul_f32 v[194:195], v[218:219], v[226:227]
	v_pk_mul_f32 v[196:197], v[220:221], v[228:229]
	v_pk_mul_f32 v[198:199], v[222:223], v[230:231]
	v_lshlrev_b32_e32 v80, 16, v116
	v_and_b32_e32 v81, 0xffff0000, v116
	v_lshlrev_b32_e32 v82, 16, v117
	v_and_b32_e32 v83, 0xffff0000, v117
	v_lshlrev_b32_e32 v84, 16, v118
	v_and_b32_e32 v85, 0xffff0000, v118
	v_lshlrev_b32_e32 v86, 16, v119
	v_and_b32_e32 v87, 0xffff0000, v119
	v_pk_mul_f32 v[64:65], v[20:21], v[200:201]
	v_pk_mul_f32 v[66:67], v[22:23], v[202:203]
	v_pk_mul_f32 v[68:69], v[16:17], v[204:205]
	v_pk_mul_f32 v[70:71], v[18:19], v[206:207]
	v_pk_mul_f32 v[72:73], v[8:9], v[208:209]
	v_pk_mul_f32 v[74:75], v[10:11], v[210:211]
	v_pk_mul_f32 v[76:77], v[0:1], v[212:213]
	v_pk_mul_f32 v[78:79], v[2:3], v[214:215]
	v_pk_add_f32 v[64:65], v[64:65], v[72:73]
	v_pk_add_f32 v[66:67], v[66:67], v[74:75]
	v_pk_add_f32 v[68:69], v[68:69], v[76:77]
	v_pk_add_f32 v[70:71], v[70:71], v[78:79]
	v_pk_fma_f32 v[64:65], v[192:193], v[12:13], v[64:65]
	v_pk_fma_f32 v[66:67], v[194:195], v[14:15], v[66:67]
	v_pk_fma_f32 v[68:69], v[196:197], v[4:5], v[68:69]
	v_pk_fma_f32 v[70:71], v[198:199], v[6:7], v[70:71]
	v_pk_mul_f32 v[64:65], v[64:65], v[80:81]
	v_pk_mul_f32 v[66:67], v[66:67], v[82:83]
	v_pk_mul_f32 v[68:69], v[68:69], v[84:85]
	v_pk_mul_f32 v[70:71], v[70:71], v[86:87]
	v_cvt_pk_bf16_f32 v232, v64, v65
	v_cvt_pk_bf16_f32 v233, v66, v67
	v_cvt_pk_bf16_f32 v234, v68, v69
	v_cvt_pk_bf16_f32 v235, v70, v71
	global_store_dwordx4 v[56:57], v[232:235], off offset:2048
	s_waitcnt vmcnt(17)
	v_lshlrev_b32_e32 v216, 16, v120
	v_and_b32_e32 v217, 0xffff0000, v120
	v_lshlrev_b32_e32 v218, 16, v121
	v_and_b32_e32 v219, 0xffff0000, v121
	v_lshlrev_b32_e32 v220, 16, v122
	v_and_b32_e32 v221, 0xffff0000, v122
	v_lshlrev_b32_e32 v222, 16, v123
	v_and_b32_e32 v223, 0xffff0000, v123
	v_lshlrev_b32_e32 v224, 16, v124
	v_and_b32_e32 v225, 0xffff0000, v124
	v_lshlrev_b32_e32 v226, 16, v125
	v_and_b32_e32 v227, 0xffff0000, v125
	v_lshlrev_b32_e32 v228, 16, v126
	v_and_b32_e32 v229, 0xffff0000, v126
	v_lshlrev_b32_e32 v230, 16, v127
	v_and_b32_e32 v231, 0xffff0000, v127
	v_pk_mul_f32 v[200:201], v[216:217], v[224:225]
	v_pk_mul_f32 v[202:203], v[218:219], v[226:227]
	v_pk_mul_f32 v[204:205], v[220:221], v[228:229]
	v_pk_mul_f32 v[206:207], v[222:223], v[230:231]
	v_lshlrev_b32_e32 v80, 16, v128
	v_and_b32_e32 v81, 0xffff0000, v128
	v_lshlrev_b32_e32 v82, 16, v129
	v_and_b32_e32 v83, 0xffff0000, v129
	v_lshlrev_b32_e32 v84, 16, v130
	v_and_b32_e32 v85, 0xffff0000, v130
	v_lshlrev_b32_e32 v86, 16, v131
	v_and_b32_e32 v87, 0xffff0000, v131
	v_pk_mul_f32 v[64:65], v[20:21], v[208:209]
	v_pk_mul_f32 v[66:67], v[22:23], v[210:211]
	v_pk_mul_f32 v[68:69], v[16:17], v[212:213]
	v_pk_mul_f32 v[70:71], v[18:19], v[214:215]
	v_pk_mul_f32 v[72:73], v[8:9], v[192:193]
	v_pk_mul_f32 v[74:75], v[10:11], v[194:195]
	v_pk_mul_f32 v[76:77], v[0:1], v[196:197]
	v_pk_mul_f32 v[78:79], v[2:3], v[198:199]
	v_pk_add_f32 v[64:65], v[64:65], v[72:73]
	v_pk_add_f32 v[66:67], v[66:67], v[74:75]
	v_pk_add_f32 v[68:69], v[68:69], v[76:77]
	v_pk_add_f32 v[70:71], v[70:71], v[78:79]
	v_pk_fma_f32 v[64:65], v[200:201], v[12:13], v[64:65]
	v_pk_fma_f32 v[66:67], v[202:203], v[14:15], v[66:67]
	v_pk_fma_f32 v[68:69], v[204:205], v[4:5], v[68:69]
	v_pk_fma_f32 v[70:71], v[206:207], v[6:7], v[70:71]
	v_pk_mul_f32 v[64:65], v[64:65], v[80:81]
	v_pk_mul_f32 v[66:67], v[66:67], v[82:83]
	v_pk_mul_f32 v[68:69], v[68:69], v[84:85]
	v_pk_mul_f32 v[70:71], v[70:71], v[86:87]
	v_cvt_pk_bf16_f32 v88, v64, v65
	v_cvt_pk_bf16_f32 v89, v66, v67
	v_cvt_pk_bf16_f32 v90, v68, v69
	v_cvt_pk_bf16_f32 v91, v70, v71
	global_store_dwordx4 v[58:59], v[88:91], off
	s_waitcnt vmcnt(15)
	v_lshlrev_b32_e32 v216, 16, v132
	v_and_b32_e32 v217, 0xffff0000, v132
	v_lshlrev_b32_e32 v218, 16, v133
	v_and_b32_e32 v219, 0xffff0000, v133
	v_lshlrev_b32_e32 v220, 16, v134
	v_and_b32_e32 v221, 0xffff0000, v134
	v_lshlrev_b32_e32 v222, 16, v135
	v_and_b32_e32 v223, 0xffff0000, v135
	v_lshlrev_b32_e32 v224, 16, v136
	v_and_b32_e32 v225, 0xffff0000, v136
	v_lshlrev_b32_e32 v226, 16, v137
	v_and_b32_e32 v227, 0xffff0000, v137
	v_lshlrev_b32_e32 v228, 16, v138
	v_and_b32_e32 v229, 0xffff0000, v138
	v_lshlrev_b32_e32 v230, 16, v139
	v_and_b32_e32 v231, 0xffff0000, v139
	v_pk_mul_f32 v[208:209], v[216:217], v[224:225]
	v_pk_mul_f32 v[210:211], v[218:219], v[226:227]
	v_pk_mul_f32 v[212:213], v[220:221], v[228:229]
	v_pk_mul_f32 v[214:215], v[222:223], v[230:231]
	v_lshlrev_b32_e32 v80, 16, v140
	v_and_b32_e32 v81, 0xffff0000, v140
	v_lshlrev_b32_e32 v82, 16, v141
	v_and_b32_e32 v83, 0xffff0000, v141
	v_lshlrev_b32_e32 v84, 16, v142
	v_and_b32_e32 v85, 0xffff0000, v142
	v_lshlrev_b32_e32 v86, 16, v143
	v_and_b32_e32 v87, 0xffff0000, v143
	v_pk_mul_f32 v[64:65], v[20:21], v[192:193]
	v_pk_mul_f32 v[66:67], v[22:23], v[194:195]
	v_pk_mul_f32 v[68:69], v[16:17], v[196:197]
	v_pk_mul_f32 v[70:71], v[18:19], v[198:199]
	v_pk_mul_f32 v[72:73], v[8:9], v[200:201]
	v_pk_mul_f32 v[74:75], v[10:11], v[202:203]
	v_pk_mul_f32 v[76:77], v[0:1], v[204:205]
	v_pk_mul_f32 v[78:79], v[2:3], v[206:207]
	v_pk_add_f32 v[64:65], v[64:65], v[72:73]
	v_pk_add_f32 v[66:67], v[66:67], v[74:75]
	v_pk_add_f32 v[68:69], v[68:69], v[76:77]
	v_pk_add_f32 v[70:71], v[70:71], v[78:79]
	v_pk_fma_f32 v[64:65], v[208:209], v[12:13], v[64:65]
	v_pk_fma_f32 v[66:67], v[210:211], v[14:15], v[66:67]
	v_pk_fma_f32 v[68:69], v[212:213], v[4:5], v[68:69]
	v_pk_fma_f32 v[70:71], v[214:215], v[6:7], v[70:71]
	v_pk_mul_f32 v[64:65], v[64:65], v[80:81]
	v_pk_mul_f32 v[66:67], v[66:67], v[82:83]
	v_pk_mul_f32 v[68:69], v[68:69], v[84:85]
	v_pk_mul_f32 v[70:71], v[70:71], v[86:87]
	v_cvt_pk_bf16_f32 v232, v64, v65
	v_cvt_pk_bf16_f32 v233, v66, v67
	v_cvt_pk_bf16_f32 v234, v68, v69
	v_cvt_pk_bf16_f32 v235, v70, v71
	global_store_dwordx4 v[58:59], v[232:235], off offset:2048
	s_waitcnt vmcnt(13)
	v_lshlrev_b32_e32 v216, 16, v144
	v_and_b32_e32 v217, 0xffff0000, v144
	v_lshlrev_b32_e32 v218, 16, v145
	v_and_b32_e32 v219, 0xffff0000, v145
	v_lshlrev_b32_e32 v220, 16, v146
	v_and_b32_e32 v221, 0xffff0000, v146
	v_lshlrev_b32_e32 v222, 16, v147
	v_and_b32_e32 v223, 0xffff0000, v147
	v_lshlrev_b32_e32 v224, 16, v148
	v_and_b32_e32 v225, 0xffff0000, v148
	v_lshlrev_b32_e32 v226, 16, v149
	v_and_b32_e32 v227, 0xffff0000, v149
	v_lshlrev_b32_e32 v228, 16, v150
	v_and_b32_e32 v229, 0xffff0000, v150
	v_lshlrev_b32_e32 v230, 16, v151
	v_and_b32_e32 v231, 0xffff0000, v151
	v_pk_mul_f32 v[192:193], v[216:217], v[224:225]
	v_pk_mul_f32 v[194:195], v[218:219], v[226:227]
	v_pk_mul_f32 v[196:197], v[220:221], v[228:229]
	v_pk_mul_f32 v[198:199], v[222:223], v[230:231]
	v_lshlrev_b32_e32 v80, 16, v152
	v_and_b32_e32 v81, 0xffff0000, v152
	v_lshlrev_b32_e32 v82, 16, v153
	v_and_b32_e32 v83, 0xffff0000, v153
	v_lshlrev_b32_e32 v84, 16, v154
	v_and_b32_e32 v85, 0xffff0000, v154
	v_lshlrev_b32_e32 v86, 16, v155
	v_and_b32_e32 v87, 0xffff0000, v155
	v_pk_mul_f32 v[64:65], v[20:21], v[200:201]
	v_pk_mul_f32 v[66:67], v[22:23], v[202:203]
	v_pk_mul_f32 v[68:69], v[16:17], v[204:205]
	v_pk_mul_f32 v[70:71], v[18:19], v[206:207]
	v_pk_mul_f32 v[72:73], v[8:9], v[208:209]
	v_pk_mul_f32 v[74:75], v[10:11], v[210:211]
	v_pk_mul_f32 v[76:77], v[0:1], v[212:213]
	v_pk_mul_f32 v[78:79], v[2:3], v[214:215]
	v_pk_add_f32 v[64:65], v[64:65], v[72:73]
	v_pk_add_f32 v[66:67], v[66:67], v[74:75]
	v_pk_add_f32 v[68:69], v[68:69], v[76:77]
	v_pk_add_f32 v[70:71], v[70:71], v[78:79]
	v_pk_fma_f32 v[64:65], v[192:193], v[12:13], v[64:65]
	v_pk_fma_f32 v[66:67], v[194:195], v[14:15], v[66:67]
	v_pk_fma_f32 v[68:69], v[196:197], v[4:5], v[68:69]
	v_pk_fma_f32 v[70:71], v[198:199], v[6:7], v[70:71]
	v_pk_mul_f32 v[64:65], v[64:65], v[80:81]
	v_pk_mul_f32 v[66:67], v[66:67], v[82:83]
	v_pk_mul_f32 v[68:69], v[68:69], v[84:85]
	v_pk_mul_f32 v[70:71], v[70:71], v[86:87]
	v_cvt_pk_bf16_f32 v88, v64, v65
	v_cvt_pk_bf16_f32 v89, v66, v67
	v_cvt_pk_bf16_f32 v90, v68, v69
	v_cvt_pk_bf16_f32 v91, v70, v71
	global_store_dwordx4 v[60:61], v[88:91], off
	s_waitcnt vmcnt(11)
	v_lshlrev_b32_e32 v216, 16, v156
	v_and_b32_e32 v217, 0xffff0000, v156
	v_lshlrev_b32_e32 v218, 16, v157
	v_and_b32_e32 v219, 0xffff0000, v157
	v_lshlrev_b32_e32 v220, 16, v158
	v_and_b32_e32 v221, 0xffff0000, v158
	v_lshlrev_b32_e32 v222, 16, v159
	v_and_b32_e32 v223, 0xffff0000, v159
	v_lshlrev_b32_e32 v224, 16, v160
	v_and_b32_e32 v225, 0xffff0000, v160
	v_lshlrev_b32_e32 v226, 16, v161
	v_and_b32_e32 v227, 0xffff0000, v161
	v_lshlrev_b32_e32 v228, 16, v162
	v_and_b32_e32 v229, 0xffff0000, v162
	v_lshlrev_b32_e32 v230, 16, v163
	v_and_b32_e32 v231, 0xffff0000, v163
	v_pk_mul_f32 v[200:201], v[216:217], v[224:225]
	v_pk_mul_f32 v[202:203], v[218:219], v[226:227]
	v_pk_mul_f32 v[204:205], v[220:221], v[228:229]
	v_pk_mul_f32 v[206:207], v[222:223], v[230:231]
	v_lshlrev_b32_e32 v80, 16, v164
	v_and_b32_e32 v81, 0xffff0000, v164
	v_lshlrev_b32_e32 v82, 16, v165
	v_and_b32_e32 v83, 0xffff0000, v165
	v_lshlrev_b32_e32 v84, 16, v166
	v_and_b32_e32 v85, 0xffff0000, v166
	v_lshlrev_b32_e32 v86, 16, v167
	v_and_b32_e32 v87, 0xffff0000, v167
	v_pk_mul_f32 v[64:65], v[20:21], v[208:209]
	v_pk_mul_f32 v[66:67], v[22:23], v[210:211]
	v_pk_mul_f32 v[68:69], v[16:17], v[212:213]
	v_pk_mul_f32 v[70:71], v[18:19], v[214:215]
	v_pk_mul_f32 v[72:73], v[8:9], v[192:193]
	v_pk_mul_f32 v[74:75], v[10:11], v[194:195]
	v_pk_mul_f32 v[76:77], v[0:1], v[196:197]
	v_pk_mul_f32 v[78:79], v[2:3], v[198:199]
	v_pk_add_f32 v[64:65], v[64:65], v[72:73]
	v_pk_add_f32 v[66:67], v[66:67], v[74:75]
	v_pk_add_f32 v[68:69], v[68:69], v[76:77]
	v_pk_add_f32 v[70:71], v[70:71], v[78:79]
	v_pk_fma_f32 v[64:65], v[200:201], v[12:13], v[64:65]
	v_pk_fma_f32 v[66:67], v[202:203], v[14:15], v[66:67]
	v_pk_fma_f32 v[68:69], v[204:205], v[4:5], v[68:69]
	v_pk_fma_f32 v[70:71], v[206:207], v[6:7], v[70:71]
	v_pk_mul_f32 v[64:65], v[64:65], v[80:81]
	v_pk_mul_f32 v[66:67], v[66:67], v[82:83]
	v_pk_mul_f32 v[68:69], v[68:69], v[84:85]
	v_pk_mul_f32 v[70:71], v[70:71], v[86:87]
	v_cvt_pk_bf16_f32 v232, v64, v65
	v_cvt_pk_bf16_f32 v233, v66, v67
	v_cvt_pk_bf16_f32 v234, v68, v69
	v_cvt_pk_bf16_f32 v235, v70, v71
	global_store_dwordx4 v[60:61], v[232:235], off offset:2048
	s_waitcnt vmcnt(9)
	v_lshlrev_b32_e32 v216, 16, v168
	v_and_b32_e32 v217, 0xffff0000, v168
	v_lshlrev_b32_e32 v218, 16, v169
	v_and_b32_e32 v219, 0xffff0000, v169
	v_lshlrev_b32_e32 v220, 16, v170
	v_and_b32_e32 v221, 0xffff0000, v170
	v_lshlrev_b32_e32 v222, 16, v171
	v_and_b32_e32 v223, 0xffff0000, v171
	v_lshlrev_b32_e32 v224, 16, v172
	v_and_b32_e32 v225, 0xffff0000, v172
	v_lshlrev_b32_e32 v226, 16, v173
	v_and_b32_e32 v227, 0xffff0000, v173
	v_lshlrev_b32_e32 v228, 16, v174
	v_and_b32_e32 v229, 0xffff0000, v174
	v_lshlrev_b32_e32 v230, 16, v175
	v_and_b32_e32 v231, 0xffff0000, v175
	v_pk_mul_f32 v[208:209], v[216:217], v[224:225]
	v_pk_mul_f32 v[210:211], v[218:219], v[226:227]
	v_pk_mul_f32 v[212:213], v[220:221], v[228:229]
	v_pk_mul_f32 v[214:215], v[222:223], v[230:231]
	v_lshlrev_b32_e32 v80, 16, v176
	v_and_b32_e32 v81, 0xffff0000, v176
	v_lshlrev_b32_e32 v82, 16, v177
	v_and_b32_e32 v83, 0xffff0000, v177
	v_lshlrev_b32_e32 v84, 16, v178
	v_and_b32_e32 v85, 0xffff0000, v178
	v_lshlrev_b32_e32 v86, 16, v179
	v_and_b32_e32 v87, 0xffff0000, v179
	v_pk_mul_f32 v[64:65], v[20:21], v[192:193]
	v_pk_mul_f32 v[66:67], v[22:23], v[194:195]
	v_pk_mul_f32 v[68:69], v[16:17], v[196:197]
	v_pk_mul_f32 v[70:71], v[18:19], v[198:199]
	v_pk_mul_f32 v[72:73], v[8:9], v[200:201]
	v_pk_mul_f32 v[74:75], v[10:11], v[202:203]
	v_pk_mul_f32 v[76:77], v[0:1], v[204:205]
	v_pk_mul_f32 v[78:79], v[2:3], v[206:207]
	v_pk_add_f32 v[64:65], v[64:65], v[72:73]
	v_pk_add_f32 v[66:67], v[66:67], v[74:75]
	v_pk_add_f32 v[68:69], v[68:69], v[76:77]
	v_pk_add_f32 v[70:71], v[70:71], v[78:79]
	v_pk_fma_f32 v[64:65], v[208:209], v[12:13], v[64:65]
	v_pk_fma_f32 v[66:67], v[210:211], v[14:15], v[66:67]
	v_pk_fma_f32 v[68:69], v[212:213], v[4:5], v[68:69]
	v_pk_fma_f32 v[70:71], v[214:215], v[6:7], v[70:71]
	v_pk_mul_f32 v[64:65], v[64:65], v[80:81]
	v_pk_mul_f32 v[66:67], v[66:67], v[82:83]
	v_pk_mul_f32 v[68:69], v[68:69], v[84:85]
	v_pk_mul_f32 v[70:71], v[70:71], v[86:87]
	v_cvt_pk_bf16_f32 v88, v64, v65
	v_cvt_pk_bf16_f32 v89, v66, v67
	v_cvt_pk_bf16_f32 v90, v68, v69
	v_cvt_pk_bf16_f32 v91, v70, v71
	global_store_dwordx4 v[62:63], v[88:91], off
	s_waitcnt vmcnt(7)
	v_lshlrev_b32_e32 v216, 16, v180
	v_and_b32_e32 v217, 0xffff0000, v180
	v_lshlrev_b32_e32 v218, 16, v181
	v_and_b32_e32 v219, 0xffff0000, v181
	v_lshlrev_b32_e32 v220, 16, v182
	v_and_b32_e32 v221, 0xffff0000, v182
	v_lshlrev_b32_e32 v222, 16, v183
	v_and_b32_e32 v223, 0xffff0000, v183
	v_lshlrev_b32_e32 v224, 16, v184
	v_and_b32_e32 v225, 0xffff0000, v184
	v_lshlrev_b32_e32 v226, 16, v185
	v_and_b32_e32 v227, 0xffff0000, v185
	v_lshlrev_b32_e32 v228, 16, v186
	v_and_b32_e32 v229, 0xffff0000, v186
	v_lshlrev_b32_e32 v230, 16, v187
	v_and_b32_e32 v231, 0xffff0000, v187
	v_pk_mul_f32 v[192:193], v[216:217], v[224:225]
	v_pk_mul_f32 v[194:195], v[218:219], v[226:227]
	v_pk_mul_f32 v[196:197], v[220:221], v[228:229]
	v_pk_mul_f32 v[198:199], v[222:223], v[230:231]
	v_lshlrev_b32_e32 v80, 16, v188
	v_and_b32_e32 v81, 0xffff0000, v188
	v_lshlrev_b32_e32 v82, 16, v189
	v_and_b32_e32 v83, 0xffff0000, v189
	v_lshlrev_b32_e32 v84, 16, v190
	v_and_b32_e32 v85, 0xffff0000, v190
	v_lshlrev_b32_e32 v86, 16, v191
	v_and_b32_e32 v87, 0xffff0000, v191
	v_pk_mul_f32 v[64:65], v[20:21], v[200:201]
	v_pk_mul_f32 v[66:67], v[22:23], v[202:203]
	v_pk_mul_f32 v[68:69], v[16:17], v[204:205]
	v_pk_mul_f32 v[70:71], v[18:19], v[206:207]
	v_pk_mul_f32 v[72:73], v[8:9], v[208:209]
	v_pk_mul_f32 v[74:75], v[10:11], v[210:211]
	v_pk_mul_f32 v[76:77], v[0:1], v[212:213]
	v_pk_mul_f32 v[78:79], v[2:3], v[214:215]
	v_pk_add_f32 v[64:65], v[64:65], v[72:73]
	v_pk_add_f32 v[66:67], v[66:67], v[74:75]
	v_pk_add_f32 v[68:69], v[68:69], v[76:77]
	v_pk_add_f32 v[70:71], v[70:71], v[78:79]
	v_pk_fma_f32 v[64:65], v[192:193], v[12:13], v[64:65]
	v_pk_fma_f32 v[66:67], v[194:195], v[14:15], v[66:67]
	v_pk_fma_f32 v[68:69], v[196:197], v[4:5], v[68:69]
	v_pk_fma_f32 v[70:71], v[198:199], v[6:7], v[70:71]
	v_pk_mul_f32 v[64:65], v[64:65], v[80:81]
	v_pk_mul_f32 v[66:67], v[66:67], v[82:83]
	v_pk_mul_f32 v[68:69], v[68:69], v[84:85]
	v_pk_mul_f32 v[70:71], v[70:71], v[86:87]
	v_cvt_pk_bf16_f32 v232, v64, v65
	v_cvt_pk_bf16_f32 v233, v66, v67
	v_cvt_pk_bf16_f32 v234, v68, v69
	v_cvt_pk_bf16_f32 v235, v70, v71
	global_store_dwordx4 v[62:63], v[232:235], off offset:2048
	s_mov_b64 s[10:11], 0

.LBB0_684:
	s_ashr_i32 s41, s40, 31
	s_lshl_b64 s[22:23], s[40:41], 19
	s_add_u32 s44, s56, s22
	s_addc_u32 s45, s57, s23
	s_and_b64 s[0:1], s[0:1], exec
	s_cselect_b32 s13, s45, s17
	s_cselect_b32 s21, s44, s16
	s_add_u32 s0, s18, 0x40080
	s_addc_u32 s1, s19, 0
	s_add_u32 s22, s16, 0x100
	v_mov_b32_e32 v36, 0
	s_addc_u32 s23, s17, 0
	s_mov_b32 s24, -2
	v_mov_b32_e32 v37, v36
	v_mov_b32_e32 v38, v36
	v_mov_b32_e32 v39, v36
	v_mov_b32_e32 v104, v36
	v_mov_b32_e32 v105, v36
	v_mov_b32_e32 v106, v36
	v_mov_b32_e32 v107, v36
	v_mov_b32_e32 v0, v36
	v_mov_b32_e32 v1, v36
	v_mov_b32_e32 v2, v36
	v_mov_b32_e32 v3, v36
	v_mov_b32_e32 v72, v36
	v_mov_b32_e32 v73, v36
	v_mov_b32_e32 v74, v36
	v_mov_b32_e32 v75, v36
	v_mov_b32_e32 v8, v36
	v_mov_b32_e32 v9, v36
	v_mov_b32_e32 v10, v36
	v_mov_b32_e32 v11, v36
	v_mov_b32_e32 v80, v36
	v_mov_b32_e32 v81, v36
	v_mov_b32_e32 v82, v36
	v_mov_b32_e32 v83, v36
	v_mov_b32_e32 v16, v36
	v_mov_b32_e32 v17, v36
	v_mov_b32_e32 v18, v36
	v_mov_b32_e32 v19, v36
	v_mov_b32_e32 v88, v36
	v_mov_b32_e32 v89, v36
	v_mov_b32_e32 v90, v36
	v_mov_b32_e32 v91, v36
	v_mov_b32_e32 v24, v36
	v_mov_b32_e32 v25, v36
	v_mov_b32_e32 v26, v36
	v_mov_b32_e32 v27, v36
	v_mov_b32_e32 v96, v36
	v_mov_b32_e32 v97, v36
	v_mov_b32_e32 v98, v36
	v_mov_b32_e32 v99, v36
	v_mov_b32_e32 v4, v36
	v_mov_b32_e32 v5, v36
	v_mov_b32_e32 v6, v36
	v_mov_b32_e32 v7, v36
	v_mov_b32_e32 v76, v36
	v_mov_b32_e32 v77, v36
	v_mov_b32_e32 v78, v36
	v_mov_b32_e32 v79, v36
	v_mov_b32_e32 v12, v36
	v_mov_b32_e32 v13, v36
	v_mov_b32_e32 v14, v36
	v_mov_b32_e32 v15, v36
	v_mov_b32_e32 v84, v36
	v_mov_b32_e32 v85, v36
	v_mov_b32_e32 v86, v36
	v_mov_b32_e32 v87, v36
	v_mov_b32_e32 v20, v36
	v_mov_b32_e32 v21, v36
	v_mov_b32_e32 v22, v36
	v_mov_b32_e32 v23, v36
	v_mov_b32_e32 v92, v36
	v_mov_b32_e32 v93, v36
	v_mov_b32_e32 v94, v36
	v_mov_b32_e32 v95, v36
	v_mov_b32_e32 v68, v36
	v_mov_b32_e32 v69, v36
	v_mov_b32_e32 v70, v36
	v_mov_b32_e32 v71, v36
	v_mov_b32_e32 v112, v36
	v_mov_b32_e32 v113, v36
	v_mov_b32_e32 v114, v36
	v_mov_b32_e32 v115, v36
	v_mov_b32_e32 v28, v36
	v_mov_b32_e32 v29, v36
	v_mov_b32_e32 v30, v36
	v_mov_b32_e32 v31, v36
	v_mov_b32_e32 v100, v36
	v_mov_b32_e32 v101, v36
	v_mov_b32_e32 v102, v36
	v_mov_b32_e32 v103, v36
	v_mov_b32_e32 v48, v36
	v_mov_b32_e32 v49, v36
	v_mov_b32_e32 v50, v36
	v_mov_b32_e32 v51, v36
	v_mov_b32_e32 v144, v36
	v_mov_b32_e32 v145, v36
	v_mov_b32_e32 v146, v36
	v_mov_b32_e32 v147, v36
	v_mov_b32_e32 v56, v36
	v_mov_b32_e32 v57, v36
	v_mov_b32_e32 v58, v36
	v_mov_b32_e32 v59, v36
	v_mov_b32_e32 v152, v36
	v_mov_b32_e32 v153, v36
	v_mov_b32_e32 v154, v36
	v_mov_b32_e32 v155, v36
	v_mov_b32_e32 v64, v36
	v_mov_b32_e32 v65, v36
	v_mov_b32_e32 v66, v36
	v_mov_b32_e32 v67, v36
	v_mov_b32_e32 v116, v36
	v_mov_b32_e32 v117, v36
	v_mov_b32_e32 v118, v36
	v_mov_b32_e32 v119, v36
	v_mov_b32_e32 v32, v36
	v_mov_b32_e32 v33, v36
	v_mov_b32_e32 v34, v36
	v_mov_b32_e32 v35, v36
	v_mov_b32_e32 v108, v36
	v_mov_b32_e32 v109, v36
	v_mov_b32_e32 v110, v36
	v_mov_b32_e32 v111, v36
	v_mov_b32_e32 v52, v36
	v_mov_b32_e32 v53, v36
	v_mov_b32_e32 v54, v36
	v_mov_b32_e32 v55, v36
	v_mov_b32_e32 v148, v36
	v_mov_b32_e32 v149, v36
	v_mov_b32_e32 v150, v36
	v_mov_b32_e32 v151, v36
	v_mov_b32_e32 v60, v36
	v_mov_b32_e32 v61, v36
	v_mov_b32_e32 v62, v36
	v_mov_b32_e32 v63, v36
	v_mov_b32_e32 v156, v36
	v_mov_b32_e32 v157, v36
	v_mov_b32_e32 v158, v36
	v_mov_b32_e32 v159, v36
